# batched loads: prologue row-convert + weight-transpose loops, res_epi residual prefetch, RSTAB single wait
# baseline (speedup 1.0000x reference)
; __device__ __forceinline__ unsigned cvt_pk_bf16(float lo, float hi) { unsigned r; asm volatile("v_cvt_pk_bf16_f32 %0, %1, %2" : "=v"(r) : "v"(lo), "v"(hi)); return r; }
; __device__ __forceinline__ void transpose_item(const float* W, int K, int N, const float* g0, const float* g1, bf16_t* WT, LAS unsigned* T, int item, int lane, bool gate_up_interleave = false, bool rope_heads = false) {
;     ...
;     const int nblk = N / 128, kb = item / nblk, nb = item % nblk, k0 = 64 * kb, n0 = 128 * nb;
;     const float* gp = g0 ? (k0 < 1024 ? g0 + k0 : g1 + (k0 - 1024)) : nullptr;
;     const int dn0 = gate_up_interleave ? ((nb < DFF / 128) ? 256 * nb : 256 * (nb - DFF / 128) + 128) : n0;
;     const int l31 = lane & 31, kh = (lane >> 5) * 2;
;     const float* wp = W + (size_t)(k0 + kh) * N + n0 + 4 * l31;
; #pragma unroll 4
;     for (int i = 0; i < 16; ++i) {
;         const int kk = 4 * i + kh;
;         f32x4 va = __builtin_nontemporal_load((const f32x4*)(wp + (size_t)(4 * i) * N)), vb = __builtin_nontemporal_load((const f32x4*)(wp + (size_t)(4 * i + 1) * N));
;         if (gp) { va = va * gp[kk]; vb = vb * gp[kk + 1]; }
; #pragma unroll
;         for (int e = 0; e < 4; ++e) T[(4 * l31 + e) * PD + (kk >> 1)] = cvt_pk_bf16(va[e], vb[e]);
;     }
.LBB0_15:
	v_lshl_add_u64 v[48:49], v[18:19], 0, s[18:19]
	s_mov_b32 s101, 0
	global_load_dwordx4 v[64:67], v[48:49], off nt
	s_mov_b32 s100, 0x4800
	v_lshl_add_u64 v[48:49], v[48:49], 0, s[100:101]
	global_load_dwordx4 v[68:71], v[48:49], off nt
	s_mov_b32 s100, 0xd800
	v_lshl_add_u64 v[48:49], v[48:49], 0, s[100:101]
	global_load_dwordx4 v[72:75], v[48:49], off nt
	s_mov_b32 s100, 0x4800
	v_lshl_add_u64 v[48:49], v[48:49], 0, s[100:101]
	global_load_dwordx4 v[76:79], v[48:49], off nt
	s_mov_b32 s100, 0xd800
	v_lshl_add_u64 v[48:49], v[48:49], 0, s[100:101]
	global_load_dwordx4 v[80:83], v[48:49], off nt
	s_mov_b32 s100, 0x4800
	v_lshl_add_u64 v[48:49], v[48:49], 0, s[100:101]
	global_load_dwordx4 v[84:87], v[48:49], off nt
	s_mov_b32 s100, 0xd800
	v_lshl_add_u64 v[48:49], v[48:49], 0, s[100:101]
	global_load_dwordx4 v[88:91], v[48:49], off nt
	s_mov_b32 s100, 0x4800
	v_lshl_add_u64 v[48:49], v[48:49], 0, s[100:101]
	global_load_dwordx4 v[92:95], v[48:49], off nt
	s_mov_b32 s100, 0xd800
	v_lshl_add_u64 v[48:49], v[48:49], 0, s[100:101]
	global_load_dwordx4 v[96:99], v[48:49], off nt
	s_mov_b32 s100, 0x4800
	v_lshl_add_u64 v[48:49], v[48:49], 0, s[100:101]
	global_load_dwordx4 v[100:103], v[48:49], off nt
	s_mov_b32 s100, 0xd800
	v_lshl_add_u64 v[48:49], v[48:49], 0, s[100:101]
	global_load_dwordx4 v[104:107], v[48:49], off nt
	s_mov_b32 s100, 0x4800
	v_lshl_add_u64 v[48:49], v[48:49], 0, s[100:101]
	global_load_dwordx4 v[108:111], v[48:49], off nt
	s_mov_b32 s100, 0xd800
	v_lshl_add_u64 v[48:49], v[48:49], 0, s[100:101]
	global_load_dwordx4 v[112:115], v[48:49], off nt
	s_mov_b32 s100, 0x4800
	v_lshl_add_u64 v[48:49], v[48:49], 0, s[100:101]
	global_load_dwordx4 v[116:119], v[48:49], off nt
	s_mov_b32 s100, 0xd800
	v_lshl_add_u64 v[48:49], v[48:49], 0, s[100:101]
	global_load_dwordx4 v[120:123], v[48:49], off nt
	s_mov_b32 s100, 0x4800
	v_lshl_add_u64 v[48:49], v[48:49], 0, s[100:101]
	global_load_dwordx4 v[124:127], v[48:49], off nt
	s_andn2_b64 vcc, exec, s[20:21]
	s_cbranch_vccnz .Ltrp_nog
	global_load_dwordx2 v[128:129], v[20:21], off offset:-52
	global_load_dwordx2 v[130:131], v[20:21], off offset:-36
	global_load_dwordx2 v[132:133], v[20:21], off offset:-20
	global_load_dwordx2 v[134:135], v[20:21], off offset:-4
	global_load_dwordx2 v[136:137], v[20:21], off offset:12
	global_load_dwordx2 v[138:139], v[20:21], off offset:28
	global_load_dwordx2 v[140:141], v[20:21], off offset:44
	global_load_dwordx2 v[142:143], v[20:21], off offset:60
	s_waitcnt vmcnt(0)
	v_pk_mul_f32 v[64:65], v[64:65], v[128:129] op_sel_hi:[1,0]
	v_pk_mul_f32 v[66:67], v[66:67], v[128:129] op_sel_hi:[1,0]
	v_pk_mul_f32 v[68:69], v[68:69], v[128:129] op_sel:[0,1]
	v_pk_mul_f32 v[70:71], v[70:71], v[128:129] op_sel:[0,1]
	v_pk_mul_f32 v[72:73], v[72:73], v[130:131] op_sel_hi:[1,0]
	v_pk_mul_f32 v[74:75], v[74:75], v[130:131] op_sel_hi:[1,0]
	v_pk_mul_f32 v[76:77], v[76:77], v[130:131] op_sel:[0,1]
	v_pk_mul_f32 v[78:79], v[78:79], v[130:131] op_sel:[0,1]
	v_pk_mul_f32 v[80:81], v[80:81], v[132:133] op_sel_hi:[1,0]
	v_pk_mul_f32 v[82:83], v[82:83], v[132:133] op_sel_hi:[1,0]
	v_pk_mul_f32 v[84:85], v[84:85], v[132:133] op_sel:[0,1]
	v_pk_mul_f32 v[86:87], v[86:87], v[132:133] op_sel:[0,1]
	v_pk_mul_f32 v[88:89], v[88:89], v[134:135] op_sel_hi:[1,0]
	v_pk_mul_f32 v[90:91], v[90:91], v[134:135] op_sel_hi:[1,0]
	v_pk_mul_f32 v[92:93], v[92:93], v[134:135] op_sel:[0,1]
	v_pk_mul_f32 v[94:95], v[94:95], v[134:135] op_sel:[0,1]
	v_pk_mul_f32 v[96:97], v[96:97], v[136:137] op_sel_hi:[1,0]
	v_pk_mul_f32 v[98:99], v[98:99], v[136:137] op_sel_hi:[1,0]
	v_pk_mul_f32 v[100:101], v[100:101], v[136:137] op_sel:[0,1]
	v_pk_mul_f32 v[102:103], v[102:103], v[136:137] op_sel:[0,1]
	v_pk_mul_f32 v[104:105], v[104:105], v[138:139] op_sel_hi:[1,0]
	v_pk_mul_f32 v[106:107], v[106:107], v[138:139] op_sel_hi:[1,0]
	v_pk_mul_f32 v[108:109], v[108:109], v[138:139] op_sel:[0,1]
	v_pk_mul_f32 v[110:111], v[110:111], v[138:139] op_sel:[0,1]
	v_pk_mul_f32 v[112:113], v[112:113], v[140:141] op_sel_hi:[1,0]
	v_pk_mul_f32 v[114:115], v[114:115], v[140:141] op_sel_hi:[1,0]
	v_pk_mul_f32 v[116:117], v[116:117], v[140:141] op_sel:[0,1]
	v_pk_mul_f32 v[118:119], v[118:119], v[140:141] op_sel:[0,1]
	v_pk_mul_f32 v[120:121], v[120:121], v[142:143] op_sel_hi:[1,0]
	v_pk_mul_f32 v[122:123], v[122:123], v[142:143] op_sel_hi:[1,0]
	v_pk_mul_f32 v[124:125], v[124:125], v[142:143] op_sel:[0,1]
	v_pk_mul_f32 v[126:127], v[126:127], v[142:143] op_sel:[0,1]
.Ltrp_nog:
	s_waitcnt vmcnt(0)
	v_cvt_pk_bf16_f32 v2, v64, v68
	ds_write_b32 v35, v2
	v_cvt_pk_bf16_f32 v3, v65, v69
	ds_write_b32 v35, v3 offset:144
	v_cvt_pk_bf16_f32 v4, v66, v70
	ds_write_b32 v35, v4 offset:288
	v_cvt_pk_bf16_f32 v5, v67, v71
	ds_write_b32 v35, v5 offset:432
	v_cvt_pk_bf16_f32 v2, v72, v76
	ds_write_b32 v35, v2 offset:8
	v_cvt_pk_bf16_f32 v3, v73, v77
	ds_write_b32 v35, v3 offset:152
	v_cvt_pk_bf16_f32 v4, v74, v78
	ds_write_b32 v35, v4 offset:296
	v_cvt_pk_bf16_f32 v5, v75, v79
	ds_write_b32 v35, v5 offset:440
	v_cvt_pk_bf16_f32 v2, v80, v84
	ds_write_b32 v35, v2 offset:16
	v_cvt_pk_bf16_f32 v3, v81, v85
	ds_write_b32 v35, v3 offset:160
	v_cvt_pk_bf16_f32 v4, v82, v86
	ds_write_b32 v35, v4 offset:304
	v_cvt_pk_bf16_f32 v5, v83, v87
	ds_write_b32 v35, v5 offset:448
	v_cvt_pk_bf16_f32 v2, v88, v92
	ds_write_b32 v35, v2 offset:24
	v_cvt_pk_bf16_f32 v3, v89, v93
	ds_write_b32 v35, v3 offset:168
	v_cvt_pk_bf16_f32 v4, v90, v94
	ds_write_b32 v35, v4 offset:312
	v_cvt_pk_bf16_f32 v5, v91, v95
	ds_write_b32 v35, v5 offset:456
	v_cvt_pk_bf16_f32 v2, v96, v100
	ds_write_b32 v35, v2 offset:32
	v_cvt_pk_bf16_f32 v3, v97, v101
	ds_write_b32 v35, v3 offset:176
	v_cvt_pk_bf16_f32 v4, v98, v102
	ds_write_b32 v35, v4 offset:320
	v_cvt_pk_bf16_f32 v5, v99, v103
	ds_write_b32 v35, v5 offset:464
	v_cvt_pk_bf16_f32 v2, v104, v108
	ds_write_b32 v35, v2 offset:40
	v_cvt_pk_bf16_f32 v3, v105, v109
	ds_write_b32 v35, v3 offset:184
	v_cvt_pk_bf16_f32 v4, v106, v110
	ds_write_b32 v35, v4 offset:328
	v_cvt_pk_bf16_f32 v5, v107, v111
	ds_write_b32 v35, v5 offset:472
	v_cvt_pk_bf16_f32 v2, v112, v116
	ds_write_b32 v35, v2 offset:48
	v_cvt_pk_bf16_f32 v3, v113, v117
	ds_write_b32 v35, v3 offset:192
	v_cvt_pk_bf16_f32 v4, v114, v118
	ds_write_b32 v35, v4 offset:336
	v_cvt_pk_bf16_f32 v5, v115, v119
	ds_write_b32 v35, v5 offset:480
	v_cvt_pk_bf16_f32 v2, v120, v124
	ds_write_b32 v35, v2 offset:56
	v_cvt_pk_bf16_f32 v3, v121, v125
	ds_write_b32 v35, v3 offset:200
	v_cvt_pk_bf16_f32 v4, v122, v126
	ds_write_b32 v35, v4 offset:344
	v_cvt_pk_bf16_f32 v5, v123, v127
	ds_write_b32 v35, v5 offset:488
	s_add_u32 s18, s18, 0x90000
	s_addc_u32 s19, s19, 0
	v_add_u32_e32 v35, 64, v35
	s_mov_b32 s100, 0x80
	v_lshl_add_u64 v[20:21], v[20:21], 0, s[100:101]
	s_cmp_eq_u32 s18, 0x120000
	s_cbranch_scc0 .LBB0_15

; __device__ __forceinline__ unsigned cvt_pk_bf16(float lo, float hi) { unsigned r; asm volatile("v_cvt_pk_bf16_f32 %0, %1, %2" : "=v"(r) : "v"(lo), "v"(hi)); return r; }
; __global__ void __launch_bounds__(NTHREADS, 2) fwd_kernel(Args a) {
;     ...
;         for (int row = gw; row < S; row += NGW) {
;             const f32x4* xr = (const f32x4*)(x_in + (size_t)row * D) + lane0;
;             u32x2* o8 = (u32x2*)(xb + (size_t)row * D) + lane0;
;             float s = 0.f;
; #pragma unroll
;             for (int j = 0; j < 8; ++j) { const f32x4 v = xr[64 * j]; s += (v[0] * v[0] + v[1] * v[1]) + (v[2] * v[2] + v[3] * v[3]); u32x2 w; w.x = cvt_pk_bf16(v[0], v[1]); w.y = cvt_pk_bf16(v[2], v[3]); o8[64 * j] = w; }
;             s = wave_sum(s, lane0);
;             if (lane0 < 32) ssq1[(size_t)row * 32 + lane0] = (lane0 == 0) ? s : 0.f;
;         }
.LBB0_51:
	v_add_co_u32_e32 v22, vcc, 0xfffff000, v4
	s_nop 1
	v_addc_co_u32_e32 v23, vcc, -1, v5, vcc
	s_waitcnt lgkmcnt(0)
	global_load_dwordx4 v[14:17], v[22:23], off offset:-3072
	global_load_dwordx4 v[18:21], v[22:23], off offset:-2048
	global_load_dwordx4 v[46:49], v[22:23], off offset:-1024
	global_load_dwordx4 v[26:29], v[4:5], off offset:-4096
	global_load_dwordx4 v[30:33], v[4:5], off offset:-3072
	global_load_dwordx4 v[34:37], v[4:5], off offset:-2048
	global_load_dwordx4 v[38:41], v[4:5], off offset:-1024
	global_load_dwordx4 v[42:45], v[4:5], off
	s_waitcnt vmcnt(0)
	v_mov_b32_e32 v22, v46
	v_mov_b32_e32 v23, v47
	v_mov_b32_e32 v24, v48
	v_mov_b32_e32 v25, v49
	v_cvt_pk_bf16_f32 v50, v14, v15
	v_cvt_pk_bf16_f32 v51, v16, v17
	global_store_dwordx2 v[6:7], v[50:51], off offset:-2048
	v_cvt_pk_bf16_f32 v52, v18, v19
	v_cvt_pk_bf16_f32 v53, v20, v21
	global_store_dwordx2 v[6:7], v[52:53], off offset:-1536
	v_cvt_pk_bf16_f32 v54, v22, v23
	v_cvt_pk_bf16_f32 v55, v24, v25
	global_store_dwordx2 v[6:7], v[54:55], off offset:-1024
	v_cvt_pk_bf16_f32 v56, v26, v27
	v_cvt_pk_bf16_f32 v57, v28, v29
	global_store_dwordx2 v[6:7], v[56:57], off offset:-512
	v_cvt_pk_bf16_f32 v58, v30, v31
	v_cvt_pk_bf16_f32 v59, v32, v33
	global_store_dwordx2 v[6:7], v[58:59], off
	v_cvt_pk_bf16_f32 v60, v34, v35
	v_cvt_pk_bf16_f32 v61, v36, v37
	global_store_dwordx2 v[6:7], v[60:61], off offset:512
	v_cvt_pk_bf16_f32 v62, v38, v39
	v_cvt_pk_bf16_f32 v63, v40, v41
	global_store_dwordx2 v[6:7], v[62:63], off offset:1024
	v_mul_f32_e32 v1, v15, v15
	v_mul_f32_e32 v15, v17, v17
	v_fmac_f32_e32 v1, v14, v14
	v_fmac_f32_e32 v15, v16, v16
	v_add_f32_e32 v1, v1, v15
	v_mul_f32_e32 v14, v19, v19
	v_mul_f32_e32 v15, v21, v21
	v_fmac_f32_e32 v14, v18, v18
	v_fmac_f32_e32 v15, v20, v20
	v_add_f32_e32 v14, v14, v15
	v_add_f32_e32 v1, v1, v14
	v_mul_f32_e32 v14, v23, v23
	v_mul_f32_e32 v15, v25, v25
	v_fmac_f32_e32 v14, v22, v22
	v_fmac_f32_e32 v15, v24, v24
	v_add_f32_e32 v14, v14, v15
	v_add_f32_e32 v1, v1, v14
	v_mul_f32_e32 v14, v27, v27
	v_mul_f32_e32 v15, v29, v29
	v_fmac_f32_e32 v14, v26, v26
	v_fmac_f32_e32 v15, v28, v28
	v_add_f32_e32 v14, v14, v15
	v_add_f32_e32 v1, v1, v14
	v_mul_f32_e32 v14, v31, v31
	v_mul_f32_e32 v15, v33, v33
	v_fmac_f32_e32 v14, v30, v30
	v_fmac_f32_e32 v15, v32, v32
	v_add_f32_e32 v14, v14, v15
	v_add_f32_e32 v1, v1, v14
	v_mul_f32_e32 v14, v35, v35
	v_mul_f32_e32 v15, v37, v37
	v_fmac_f32_e32 v14, v34, v34
	v_fmac_f32_e32 v15, v36, v36
	v_add_f32_e32 v14, v14, v15
	v_add_f32_e32 v1, v1, v14
	v_mul_f32_e32 v14, v39, v39
	v_mul_f32_e32 v15, v41, v41
	v_fmac_f32_e32 v14, v38, v38
	v_fmac_f32_e32 v15, v40, v40
	v_add_f32_e32 v14, v14, v15
	v_add_f32_e32 v1, v1, v14
	v_mul_f32_e32 v14, v43, v43
	v_mul_f32_e32 v15, v45, v45
	v_fmac_f32_e32 v14, v42, v42
	v_fmac_f32_e32 v15, v44, v44
	v_add_f32_e32 v14, v14, v15
	v_add_f32_e32 v1, v1, v14
	ds_bpermute_b32 v14, v8, v1
	v_cvt_pk_bf16_f32 v16, v42, v43
	v_cvt_pk_bf16_f32 v17, v44, v45
	global_store_dwordx2 v[6:7], v[16:17], off offset:1536
	s_waitcnt lgkmcnt(0)
	v_add_f32_e32 v1, v1, v14
	ds_bpermute_b32 v14, v9, v1
	s_waitcnt lgkmcnt(0)
	v_add_f32_e32 v1, v1, v14
	ds_bpermute_b32 v14, v10, v1
	s_waitcnt lgkmcnt(0)
	v_add_f32_e32 v1, v1, v14
	ds_bpermute_b32 v14, v11, v1
	s_waitcnt lgkmcnt(0)
	v_add_f32_e32 v1, v1, v14
	ds_bpermute_b32 v14, v12, v1
	s_waitcnt lgkmcnt(0)
	v_add_f32_e32 v1, v1, v14
	ds_bpermute_b32 v14, v13, v1
	s_and_saveexec_b64 s[20:21], s[6:7]
	s_cbranch_execz .LBB0_50
	s_waitcnt lgkmcnt(0)
	v_add_f32_e32 v1, v1, v14
	v_cndmask_b32_e64 v1, 0, v1, s[4:5]
	global_store_dword v[2:3], v1, off
	s_branch .LBB0_50

; __device__ __forceinline__ unsigned cvt_pk_bf16(float lo, float hi) { unsigned r; asm volatile("v_cvt_pk_bf16_f32 %0, %1, %2" : "=v"(r) : "v"(lo), "v"(hi)); return r; }
; __device__ __forceinline__ float bflo(unsigned u) { return __uint_as_float(u << 16); }
; __device__ __forceinline__ float bfhi(unsigned u) { return __uint_as_float(u & 0xffff0000u); }
; template <bool F32OUT>
; __device__ __forceinline__ void res_epi(const f32x4 (&acc)[2][2][4][2], int pm, int pn, int wr, int wc, int fr, int fq, bf16_t* xb, float* xout, float* ssq_next) {
;     const int row0 = pm * BM + wr * 64 + fr, col0 = pn * BM + wc * 32 + 8 * fq, ln = (fq << 4) | fr;
; #pragma unroll
;     for (int ai = 0; ai < 2; ++ai) {
; #pragma unroll
;         for (int m = 0; m < 4; ++m) {
;             const int row = row0 + ai * HALF + m * 16;
;             const size_t off = (size_t)row * D + col0;
;             u32x4 r[2];
; #pragma unroll
;             for (int bj = 0; bj < 2; ++bj) r[bj] = *(const u32x4*)(xb + off + bj * HALF);
;             float s = 0.f;
; #pragma unroll
;             for (int bj = 0; bj < 2; ++bj) {
;                 f32x4 v0 = acc[ai][bj][m][0], v1 = acc[ai][bj][m][1];
;                 v0[0] += bflo(r[bj].x); v0[1] += bfhi(r[bj].x); v0[2] += bflo(r[bj].y); v0[3] += bfhi(r[bj].y);
;                 v1[0] += bflo(r[bj].z); v1[1] += bfhi(r[bj].z); v1[2] += bflo(r[bj].w); v1[3] += bfhi(r[bj].w);
;                 if (F32OUT) { *(f32x4*)(xout + off + bj * HALF) = v0; *(f32x4*)(xout + off + bj * HALF + 4) = v1; }
;                 s += ((v0[0] * v0[0] + v0[1] * v0[1]) + (v0[2] * v0[2] + v0[3] * v0[3])) + ((v1[0] * v1[0] + v1[1] * v1[1]) + (v1[2] * v1[2] + v1[3] * v1[3]));
;                 u32x4 w; w.x = cvt_pk_bf16(v0[0], v0[1]); w.y = cvt_pk_bf16(v0[2], v0[3]); w.z = cvt_pk_bf16(v1[0], v1[1]); w.w = cvt_pk_bf16(v1[2], v1[3]);
;                 if (!F32OUT) *(u32x4*)(xb + off + bj * HALF) = w;
.LBB0_258:
	s_andn2_b64 vcc, exec, s[0:1]
	s_cbranch_vccnz .LBB0_260
	s_lshl_b32 s0, s27, 8
	s_add_i32 s0, s0, s53
	v_or_b32_e32 v130, s0, v213
	s_lshl_b32 s0, s22, 8
	v_lshl_or_b32 v0, v214, 3, s0
	v_lshlrev_b32_e32 v131, 6, v214
	v_lshlrev_b32_e32 v134, 2, v213
	s_movk_i32 s0, 0x80
	v_or_b32_e32 v132, s50, v0
	v_bitop3_b32 v0, v131, 64, v134 bitop3:0x36
	v_bitop3_b32 v134, v131, s0, v134 bitop3:0x36
	v_ashrrev_i32_e32 v131, 31, v130
	v_ashrrev_i32_e32 v133, 31, v132
	v_lshlrev_b64 v[136:137], 12, v[130:131]
	v_lshl_add_u64 v[136:137], s[4:5], 0, v[136:137]
	v_lshlrev_b64 v[132:133], 1, v[132:133]
	v_lshl_add_u64 v[144:145], v[136:137], 0, v[132:133]
	s_mov_b32 s100, 0x10000
	s_mov_b32 s101, 0
	global_load_dwordx4 v[146:149], v[144:145], off
	global_load_dwordx4 v[150:153], v[144:145], off offset:256
	v_lshl_add_u64 v[202:203], v[144:145], 0, s[100:101]
	global_load_dwordx4 v[154:157], v[202:203], off
	global_load_dwordx4 v[158:161], v[202:203], off offset:256
	v_lshl_add_u64 v[202:203], v[202:203], 0, s[100:101]
	global_load_dwordx4 v[162:165], v[202:203], off
	global_load_dwordx4 v[166:169], v[202:203], off offset:256
	v_lshl_add_u64 v[202:203], v[202:203], 0, s[100:101]
	global_load_dwordx4 v[170:173], v[202:203], off
	global_load_dwordx4 v[174:177], v[202:203], off offset:256
	s_mov_b32 s100, 0x50000
	v_lshl_add_u64 v[202:203], v[202:203], 0, s[100:101]
	s_mov_b32 s100, 0x10000
	global_load_dwordx4 v[178:181], v[202:203], off
	global_load_dwordx4 v[182:185], v[202:203], off offset:256
	v_lshl_add_u64 v[202:203], v[202:203], 0, s[100:101]
	global_load_dwordx4 v[198:201], v[202:203], off
	global_load_dwordx4 v[216:219], v[202:203], off offset:256
	v_lshl_add_u64 v[202:203], v[202:203], 0, s[100:101]
	global_load_dwordx4 v[220:223], v[202:203], off
	global_load_dwordx4 v[224:227], v[202:203], off offset:256
	v_lshl_add_u64 v[202:203], v[202:203], 0, s[100:101]
	global_load_dwordx4 v[228:231], v[202:203], off
	global_load_dwordx4 v[232:235], v[202:203], off offset:256
	s_lshl_b32 s0, s22, 2
	s_ashr_i32 s1, s0, 31
	s_lshl_b64 s[0:1], s[0:1], 2
	v_readlane_b32 s16, v236, 52
	s_add_u32 s0, s16, s0
	v_readlane_b32 s16, v236, 53
	s_addc_u32 s1, s16, s1
	s_waitcnt vmcnt(14)
	v_mov_b32_e32 v136, v146
	v_mov_b32_e32 v137, v147
	v_mov_b32_e32 v138, v148
	v_mov_b32_e32 v139, v149
	v_mov_b32_e32 v140, v150
	v_mov_b32_e32 v141, v151
	v_mov_b32_e32 v142, v152
	v_mov_b32_e32 v143, v153
	v_lshlrev_b32_e32 v135, 16, v136
	v_add_f32_e32 v126, v126, v135
	v_and_b32_e32 v135, 0xffff0000, v136
	v_add_f32_e32 v127, v127, v135
	v_lshlrev_b32_e32 v135, 16, v137
	v_add_f32_e32 v128, v128, v135
	v_and_b32_e32 v135, 0xffff0000, v137
	v_add_f32_e32 v129, v129, v135
	v_lshlrev_b32_e32 v135, 16, v138
	v_add_f32_e32 v135, v122, v135
	v_and_b32_e32 v122, 0xffff0000, v138
	v_add_f32_e32 v136, v123, v122
	v_lshlrev_b32_e32 v122, 16, v139
	v_add_f32_e32 v137, v124, v122
	v_and_b32_e32 v122, 0xffff0000, v139
	v_add_f32_e32 v125, v125, v122
	v_mul_f32_e32 v122, v127, v127
	v_mul_f32_e32 v123, v129, v129
	v_fmac_f32_e32 v122, v126, v126
	v_fmac_f32_e32 v123, v128, v128
	v_add_f32_e32 v122, v122, v123
	v_mul_f32_e32 v123, v136, v136
	v_mul_f32_e32 v124, v125, v125
	v_fmac_f32_e32 v123, v135, v135
	v_fmac_f32_e32 v124, v137, v137
	v_add_f32_e32 v123, v123, v124
	v_add_f32_e32 v138, v122, v123
	v_cvt_pk_bf16_f32 v122, v126, v127
	v_cvt_pk_bf16_f32 v123, v128, v129
	v_cvt_pk_bf16_f32 v124, v135, v136
	v_cvt_pk_bf16_f32 v125, v137, v125
	global_store_dwordx4 v[144:145], v[122:125], off
	s_nop 1
	v_lshlrev_b32_e32 v122, 16, v140
	v_add_f32_e32 v118, v118, v122
	v_and_b32_e32 v122, 0xffff0000, v140
	v_add_f32_e32 v119, v119, v122
	v_lshlrev_b32_e32 v122, 16, v141
	v_add_f32_e32 v120, v120, v122
	v_and_b32_e32 v122, 0xffff0000, v141
	v_add_f32_e32 v121, v121, v122
	v_lshlrev_b32_e32 v122, 16, v142
	v_add_f32_e32 v122, v114, v122
	v_and_b32_e32 v114, 0xffff0000, v142
	v_add_f32_e32 v123, v115, v114
	v_lshlrev_b32_e32 v114, 16, v143
	v_add_f32_e32 v124, v116, v114
	v_and_b32_e32 v114, 0xffff0000, v143
	v_add_f32_e32 v117, v117, v114
	v_mul_f32_e32 v114, v119, v119
	v_mul_f32_e32 v115, v121, v121
	v_fmac_f32_e32 v114, v118, v118
	v_fmac_f32_e32 v115, v120, v120
	v_add_f32_e32 v114, v114, v115
	v_mul_f32_e32 v115, v123, v123
	v_mul_f32_e32 v116, v117, v117
	v_fmac_f32_e32 v115, v122, v122
	v_fmac_f32_e32 v116, v124, v124
	v_add_f32_e32 v115, v115, v116
	v_add_f32_e32 v114, v114, v115
	v_add_f32_e32 v125, v138, v114
	v_cvt_pk_bf16_f32 v114, v118, v119
	v_cvt_pk_bf16_f32 v115, v120, v121
	v_cvt_pk_bf16_f32 v116, v122, v123
	v_cvt_pk_bf16_f32 v117, v124, v117
	global_store_dwordx4 v[144:145], v[114:117], off offset:256
	ds_bpermute_b32 v114, v0, v125
	s_waitcnt lgkmcnt(0)
	v_add_f32_e32 v114, v125, v114
	ds_bpermute_b32 v115, v134, v114
	s_waitcnt lgkmcnt(0)
	v_add_f32_e32 v116, v114, v115
	v_lshlrev_b64 v[114:115], 7, v[130:131]
	v_lshl_add_u64 v[114:115], s[0:1], 0, v[114:115]
	global_store_dword v[114:115], v116, off
	v_or_b32_e32 v114, 16, v130
	v_ashrrev_i32_e32 v115, 31, v114
	v_lshlrev_b64 v[116:117], 12, v[114:115]
	v_lshl_add_u64 v[116:117], s[4:5], 0, v[116:117]
	v_lshl_add_u64 v[116:117], v[116:117], 0, v[132:133]
	s_waitcnt vmcnt(15)
; __device__ __forceinline__ unsigned cvt_pk_bf16(float lo, float hi) { unsigned r; asm volatile("v_cvt_pk_bf16_f32 %0, %1, %2" : "=v"(r) : "v"(lo), "v"(hi)); return r; }
; __device__ __forceinline__ float bflo(unsigned u) { return __uint_as_float(u << 16); }
; __device__ __forceinline__ float bfhi(unsigned u) { return __uint_as_float(u & 0xffff0000u); }
; __device__ __forceinline__ float shfl_xor_l(float v, int mask, int lane) { return __builtin_bit_cast(float, __builtin_amdgcn_ds_bpermute((lane ^ mask) << 2, __builtin_bit_cast(int, v))); }
; template <bool F32OUT>
; __device__ __forceinline__ void res_epi(const f32x4 (&acc)[2][2][4][2], int pm, int pn, int wr, int wc, int fr, int fq, bf16_t* xb, float* xout, float* ssq_next) {
;     ...
;         for (int m = 0; m < 4; ++m) {
;             const int row = row0 + ai * HALF + m * 16;
;             const size_t off = (size_t)row * D + col0;
;             u32x4 r[2];
; #pragma unroll
;             for (int bj = 0; bj < 2; ++bj) r[bj] = *(const u32x4*)(xb + off + bj * HALF);
;             float s = 0.f;
; #pragma unroll
;             for (int bj = 0; bj < 2; ++bj) {
;                 f32x4 v0 = acc[ai][bj][m][0], v1 = acc[ai][bj][m][1];
;                 v0[0] += bflo(r[bj].x); v0[1] += bfhi(r[bj].x); v0[2] += bflo(r[bj].y); v0[3] += bfhi(r[bj].y);
;                 v1[0] += bflo(r[bj].z); v1[1] += bfhi(r[bj].z); v1[2] += bflo(r[bj].w); v1[3] += bfhi(r[bj].w);
;                 if (F32OUT) { *(f32x4*)(xout + off + bj * HALF) = v0; *(f32x4*)(xout + off + bj * HALF + 4) = v1; }
;                 s += ((v0[0] * v0[0] + v0[1] * v0[1]) + (v0[2] * v0[2] + v0[3] * v0[3])) + ((v1[0] * v1[0] + v1[1] * v1[1]) + (v1[2] * v1[2] + v1[3] * v1[3]));
;                 u32x4 w; w.x = cvt_pk_bf16(v0[0], v0[1]); w.y = cvt_pk_bf16(v0[2], v0[3]); w.z = cvt_pk_bf16(v1[0], v1[1]); w.w = cvt_pk_bf16(v1[2], v1[3]);
;                 if (!F32OUT) *(u32x4*)(xb + off + bj * HALF) = w;
;             }
;             if (!F32OUT) { s += shfl_xor_l(s, 16, ln); s += shfl_xor_l(s, 32, ln);
;                 ssq_next[(size_t)row * 32 + pn * 4 + wc] = s; }
	v_mov_b32_e32 v118, v154
	v_mov_b32_e32 v119, v155
	v_mov_b32_e32 v120, v156
	v_mov_b32_e32 v121, v157
	v_mov_b32_e32 v122, v158
	v_mov_b32_e32 v123, v159
	v_mov_b32_e32 v124, v160
	v_mov_b32_e32 v125, v161
	v_lshlrev_b32_e32 v126, 16, v118
	v_and_b32_e32 v118, 0xffff0000, v118
	v_add_f32_e32 v111, v111, v118
	v_lshlrev_b32_e32 v118, 16, v119
	v_add_f32_e32 v112, v112, v118
	v_and_b32_e32 v118, 0xffff0000, v119
	v_add_f32_e32 v113, v113, v118
	v_lshlrev_b32_e32 v118, 16, v120
	v_add_f32_e32 v118, v106, v118
	v_and_b32_e32 v106, 0xffff0000, v120
	v_add_f32_e32 v119, v107, v106
	v_lshlrev_b32_e32 v106, 16, v121
	v_add_f32_e32 v120, v108, v106
	v_and_b32_e32 v106, 0xffff0000, v121
	v_add_f32_e32 v110, v110, v126
	v_add_f32_e32 v109, v109, v106
	v_mul_f32_e32 v106, v111, v111
	v_mul_f32_e32 v107, v113, v113
	v_fmac_f32_e32 v106, v110, v110
	v_fmac_f32_e32 v107, v112, v112
	v_add_f32_e32 v106, v106, v107
	v_mul_f32_e32 v107, v119, v119
	v_mul_f32_e32 v108, v109, v109
	v_fmac_f32_e32 v107, v118, v118
	v_fmac_f32_e32 v108, v120, v120
	v_add_f32_e32 v107, v107, v108
	v_add_f32_e32 v121, v106, v107
	v_cvt_pk_bf16_f32 v106, v110, v111
	v_cvt_pk_bf16_f32 v107, v112, v113
	v_cvt_pk_bf16_f32 v108, v118, v119
	v_cvt_pk_bf16_f32 v109, v120, v109
	global_store_dwordx4 v[116:117], v[106:109], off
	s_nop 0
	v_lshlrev_b32_e32 v106, 16, v122
	v_add_f32_e32 v102, v102, v106
	v_and_b32_e32 v106, 0xffff0000, v122
	v_add_f32_e32 v103, v103, v106
	v_lshlrev_b32_e32 v106, 16, v123
	v_add_f32_e32 v104, v104, v106
	v_and_b32_e32 v106, 0xffff0000, v123
	v_add_f32_e32 v105, v105, v106
	v_lshlrev_b32_e32 v106, 16, v124
	v_add_f32_e32 v106, v98, v106
	v_and_b32_e32 v98, 0xffff0000, v124
	v_add_f32_e32 v107, v99, v98
	v_lshlrev_b32_e32 v98, 16, v125
	v_add_f32_e32 v108, v100, v98
	v_and_b32_e32 v98, 0xffff0000, v125
	v_add_f32_e32 v101, v101, v98
	v_mul_f32_e32 v98, v103, v103
	v_mul_f32_e32 v99, v105, v105
	v_fmac_f32_e32 v98, v102, v102
	v_fmac_f32_e32 v99, v104, v104
	v_add_f32_e32 v98, v98, v99
	v_mul_f32_e32 v99, v107, v107
	v_mul_f32_e32 v100, v101, v101
	v_fmac_f32_e32 v99, v106, v106
	v_fmac_f32_e32 v100, v108, v108
	v_add_f32_e32 v99, v99, v100
	v_add_f32_e32 v98, v98, v99
	v_add_f32_e32 v109, v121, v98
	v_cvt_pk_bf16_f32 v98, v102, v103
	v_cvt_pk_bf16_f32 v99, v104, v105
	v_cvt_pk_bf16_f32 v100, v106, v107
	v_cvt_pk_bf16_f32 v101, v108, v101
	global_store_dwordx4 v[116:117], v[98:101], off offset:256
	ds_bpermute_b32 v98, v0, v109
	s_waitcnt lgkmcnt(0)
	v_add_f32_e32 v98, v109, v98
	ds_bpermute_b32 v99, v134, v98
	s_waitcnt lgkmcnt(0)
	v_add_f32_e32 v100, v98, v99
	v_lshlrev_b64 v[98:99], 7, v[114:115]
	v_lshl_add_u64 v[98:99], s[0:1], 0, v[98:99]
	global_store_dword v[98:99], v100, off
	v_or_b32_e32 v98, 32, v130
	v_ashrrev_i32_e32 v99, 31, v98
	v_lshlrev_b64 v[100:101], 12, v[98:99]
	v_lshl_add_u64 v[100:101], s[4:5], 0, v[100:101]
	v_lshl_add_u64 v[100:101], v[100:101], 0, v[132:133]
	s_waitcnt vmcnt(16)
	v_mov_b32_e32 v102, v162
	v_mov_b32_e32 v103, v163
	v_mov_b32_e32 v104, v164
	v_mov_b32_e32 v105, v165
	v_mov_b32_e32 v106, v166
	v_mov_b32_e32 v107, v167
	v_mov_b32_e32 v108, v168
	v_mov_b32_e32 v109, v169
	v_lshlrev_b32_e32 v110, 16, v102
	v_and_b32_e32 v102, 0xffff0000, v102
	v_add_f32_e32 v95, v95, v102
	v_lshlrev_b32_e32 v102, 16, v103
	v_add_f32_e32 v96, v96, v102
	v_and_b32_e32 v102, 0xffff0000, v103
	v_add_f32_e32 v97, v97, v102
	v_lshlrev_b32_e32 v102, 16, v104
	v_add_f32_e32 v102, v90, v102
	v_and_b32_e32 v90, 0xffff0000, v104
	v_add_f32_e32 v103, v91, v90
	v_lshlrev_b32_e32 v90, 16, v105
	v_add_f32_e32 v104, v92, v90
	v_and_b32_e32 v90, 0xffff0000, v105
	v_add_f32_e32 v94, v94, v110
	v_add_f32_e32 v93, v93, v90
	v_mul_f32_e32 v90, v95, v95
	v_mul_f32_e32 v91, v97, v97
	v_fmac_f32_e32 v90, v94, v94
	v_fmac_f32_e32 v91, v96, v96
	v_add_f32_e32 v90, v90, v91
	v_mul_f32_e32 v91, v103, v103
	v_mul_f32_e32 v92, v93, v93
	v_fmac_f32_e32 v91, v102, v102
	v_fmac_f32_e32 v92, v104, v104
	v_add_f32_e32 v91, v91, v92
	v_add_f32_e32 v105, v90, v91
	v_cvt_pk_bf16_f32 v90, v94, v95
	v_cvt_pk_bf16_f32 v91, v96, v97
	v_cvt_pk_bf16_f32 v92, v102, v103
	v_cvt_pk_bf16_f32 v93, v104, v93
	global_store_dwordx4 v[100:101], v[90:93], off
	s_nop 0
	v_lshlrev_b32_e32 v90, 16, v106
	v_add_f32_e32 v86, v86, v90
	v_and_b32_e32 v90, 0xffff0000, v106
	v_add_f32_e32 v87, v87, v90
	v_lshlrev_b32_e32 v90, 16, v107
	v_add_f32_e32 v88, v88, v90
	v_and_b32_e32 v90, 0xffff0000, v107
	v_add_f32_e32 v89, v89, v90
	v_lshlrev_b32_e32 v90, 16, v108
	v_add_f32_e32 v90, v82, v90
	v_and_b32_e32 v82, 0xffff0000, v108
	v_add_f32_e32 v91, v83, v82
	v_lshlrev_b32_e32 v82, 16, v109
	v_add_f32_e32 v92, v84, v82
	v_and_b32_e32 v82, 0xffff0000, v109
	v_add_f32_e32 v85, v85, v82
	v_mul_f32_e32 v82, v87, v87
	v_mul_f32_e32 v83, v89, v89
	v_fmac_f32_e32 v82, v86, v86
	v_fmac_f32_e32 v83, v88, v88
	v_add_f32_e32 v82, v82, v83
	v_mul_f32_e32 v83, v91, v91
	v_mul_f32_e32 v84, v85, v85
	v_fmac_f32_e32 v83, v90, v90
	v_fmac_f32_e32 v84, v92, v92
	v_add_f32_e32 v83, v83, v84
	v_add_f32_e32 v82, v82, v83
	v_add_f32_e32 v93, v105, v82
	v_cvt_pk_bf16_f32 v82, v86, v87
	v_cvt_pk_bf16_f32 v83, v88, v89
	v_cvt_pk_bf16_f32 v84, v90, v91
	v_cvt_pk_bf16_f32 v85, v92, v85
	global_store_dwordx4 v[100:101], v[82:85], off offset:256
	ds_bpermute_b32 v82, v0, v93
	s_waitcnt lgkmcnt(0)
	v_add_f32_e32 v82, v93, v82
	ds_bpermute_b32 v83, v134, v82
	s_waitcnt lgkmcnt(0)
	v_add_f32_e32 v84, v82, v83
	v_lshlrev_b64 v[82:83], 7, v[98:99]
	v_lshl_add_u64 v[82:83], s[0:1], 0, v[82:83]
	global_store_dword v[82:83], v84, off
	v_or_b32_e32 v82, 48, v130
	v_ashrrev_i32_e32 v83, 31, v82
	v_lshlrev_b64 v[84:85], 12, v[82:83]
	v_lshl_add_u64 v[84:85], s[4:5], 0, v[84:85]
	v_lshl_add_u64 v[84:85], v[84:85], 0, v[132:133]
	s_waitcnt vmcnt(17)
; __device__ __forceinline__ unsigned cvt_pk_bf16(float lo, float hi) { unsigned r; asm volatile("v_cvt_pk_bf16_f32 %0, %1, %2" : "=v"(r) : "v"(lo), "v"(hi)); return r; }
; __device__ __forceinline__ float bflo(unsigned u) { return __uint_as_float(u << 16); }
; __device__ __forceinline__ float bfhi(unsigned u) { return __uint_as_float(u & 0xffff0000u); }
; __device__ __forceinline__ float shfl_xor_l(float v, int mask, int lane) { return __builtin_bit_cast(float, __builtin_amdgcn_ds_bpermute((lane ^ mask) << 2, __builtin_bit_cast(int, v))); }
; template <bool F32OUT>
; __device__ __forceinline__ void res_epi(const f32x4 (&acc)[2][2][4][2], int pm, int pn, int wr, int wc, int fr, int fq, bf16_t* xb, float* xout, float* ssq_next) {
;     ...
;         for (int m = 0; m < 4; ++m) {
;             const int row = row0 + ai * HALF + m * 16;
;             const size_t off = (size_t)row * D + col0;
;             u32x4 r[2];
; #pragma unroll
;             for (int bj = 0; bj < 2; ++bj) r[bj] = *(const u32x4*)(xb + off + bj * HALF);
;             float s = 0.f;
; #pragma unroll
;             for (int bj = 0; bj < 2; ++bj) {
;                 f32x4 v0 = acc[ai][bj][m][0], v1 = acc[ai][bj][m][1];
;                 v0[0] += bflo(r[bj].x); v0[1] += bfhi(r[bj].x); v0[2] += bflo(r[bj].y); v0[3] += bfhi(r[bj].y);
;                 v1[0] += bflo(r[bj].z); v1[1] += bfhi(r[bj].z); v1[2] += bflo(r[bj].w); v1[3] += bfhi(r[bj].w);
;                 if (F32OUT) { *(f32x4*)(xout + off + bj * HALF) = v0; *(f32x4*)(xout + off + bj * HALF + 4) = v1; }
;                 s += ((v0[0] * v0[0] + v0[1] * v0[1]) + (v0[2] * v0[2] + v0[3] * v0[3])) + ((v1[0] * v1[0] + v1[1] * v1[1]) + (v1[2] * v1[2] + v1[3] * v1[3]));
;                 u32x4 w; w.x = cvt_pk_bf16(v0[0], v0[1]); w.y = cvt_pk_bf16(v0[2], v0[3]); w.z = cvt_pk_bf16(v1[0], v1[1]); w.w = cvt_pk_bf16(v1[2], v1[3]);
;                 if (!F32OUT) *(u32x4*)(xb + off + bj * HALF) = w;
;             }
;             if (!F32OUT) { s += shfl_xor_l(s, 16, ln); s += shfl_xor_l(s, 32, ln);
;                 ssq_next[(size_t)row * 32 + pn * 4 + wc] = s; }
	v_mov_b32_e32 v86, v170
	v_mov_b32_e32 v87, v171
	v_mov_b32_e32 v88, v172
	v_mov_b32_e32 v89, v173
	v_mov_b32_e32 v90, v174
	v_mov_b32_e32 v91, v175
	v_mov_b32_e32 v92, v176
	v_mov_b32_e32 v93, v177
	v_lshlrev_b32_e32 v94, 16, v86
	v_and_b32_e32 v86, 0xffff0000, v86
	v_add_f32_e32 v79, v79, v86
	v_lshlrev_b32_e32 v86, 16, v87
	v_add_f32_e32 v80, v80, v86
	v_and_b32_e32 v86, 0xffff0000, v87
	v_add_f32_e32 v81, v81, v86
	v_lshlrev_b32_e32 v86, 16, v88
	v_add_f32_e32 v86, v74, v86
	v_and_b32_e32 v74, 0xffff0000, v88
	v_add_f32_e32 v87, v75, v74
	v_lshlrev_b32_e32 v74, 16, v89
	v_add_f32_e32 v88, v76, v74
	v_and_b32_e32 v74, 0xffff0000, v89
	v_add_f32_e32 v78, v78, v94
	v_add_f32_e32 v77, v77, v74
	v_mul_f32_e32 v74, v79, v79
	v_mul_f32_e32 v75, v81, v81
	v_fmac_f32_e32 v74, v78, v78
	v_fmac_f32_e32 v75, v80, v80
	v_add_f32_e32 v74, v74, v75
	v_mul_f32_e32 v75, v87, v87
	v_mul_f32_e32 v76, v77, v77
	v_fmac_f32_e32 v75, v86, v86
	v_fmac_f32_e32 v76, v88, v88
	v_add_f32_e32 v75, v75, v76
	v_add_f32_e32 v89, v74, v75
	v_cvt_pk_bf16_f32 v74, v78, v79
	v_cvt_pk_bf16_f32 v75, v80, v81
	v_cvt_pk_bf16_f32 v76, v86, v87
	v_cvt_pk_bf16_f32 v77, v88, v77
	global_store_dwordx4 v[84:85], v[74:77], off
	s_nop 0
	v_lshlrev_b32_e32 v74, 16, v90
	v_add_f32_e32 v70, v70, v74
	v_and_b32_e32 v74, 0xffff0000, v90
	v_add_f32_e32 v71, v71, v74
	v_lshlrev_b32_e32 v74, 16, v91
	v_add_f32_e32 v72, v72, v74
	v_and_b32_e32 v74, 0xffff0000, v91
	v_add_f32_e32 v73, v73, v74
	v_lshlrev_b32_e32 v74, 16, v92
	v_add_f32_e32 v74, v66, v74
	v_and_b32_e32 v66, 0xffff0000, v92
	v_add_f32_e32 v75, v67, v66
	v_lshlrev_b32_e32 v66, 16, v93
	v_add_f32_e32 v76, v68, v66
	v_and_b32_e32 v66, 0xffff0000, v93
	v_add_f32_e32 v69, v69, v66
	v_mul_f32_e32 v66, v71, v71
	v_mul_f32_e32 v67, v73, v73
	v_fmac_f32_e32 v66, v70, v70
	v_fmac_f32_e32 v67, v72, v72
	v_add_f32_e32 v66, v66, v67
	v_mul_f32_e32 v67, v75, v75
	v_mul_f32_e32 v68, v69, v69
	v_fmac_f32_e32 v67, v74, v74
	v_fmac_f32_e32 v68, v76, v76
	v_add_f32_e32 v67, v67, v68
	v_add_f32_e32 v66, v66, v67
	v_add_f32_e32 v77, v89, v66
	v_cvt_pk_bf16_f32 v66, v70, v71
	v_cvt_pk_bf16_f32 v67, v72, v73
	v_cvt_pk_bf16_f32 v68, v74, v75
	v_cvt_pk_bf16_f32 v69, v76, v69
	global_store_dwordx4 v[84:85], v[66:69], off offset:256
	ds_bpermute_b32 v66, v0, v77
	s_waitcnt lgkmcnt(0)
	v_add_f32_e32 v66, v77, v66
	ds_bpermute_b32 v67, v134, v66
	s_waitcnt lgkmcnt(0)
	v_add_f32_e32 v68, v66, v67
	v_lshlrev_b64 v[66:67], 7, v[82:83]
	v_lshl_add_u64 v[66:67], s[0:1], 0, v[66:67]
	global_store_dword v[66:67], v68, off
	v_add_u32_e32 v66, 0x80, v130
	v_ashrrev_i32_e32 v67, 31, v66
	v_lshlrev_b64 v[68:69], 12, v[66:67]
	v_lshl_add_u64 v[68:69], s[4:5], 0, v[68:69]
	v_lshl_add_u64 v[68:69], v[68:69], 0, v[132:133]
	s_waitcnt vmcnt(18)
	v_mov_b32_e32 v70, v178
	v_mov_b32_e32 v71, v179
	v_mov_b32_e32 v72, v180
	v_mov_b32_e32 v73, v181
	v_mov_b32_e32 v74, v182
	v_mov_b32_e32 v75, v183
	v_mov_b32_e32 v76, v184
	v_mov_b32_e32 v77, v185
	v_lshlrev_b32_e32 v78, 16, v70
	v_and_b32_e32 v70, 0xffff0000, v70
	v_add_f32_e32 v63, v63, v70
	v_lshlrev_b32_e32 v70, 16, v71
	v_add_f32_e32 v64, v64, v70
	v_and_b32_e32 v70, 0xffff0000, v71
	v_add_f32_e32 v65, v65, v70
	v_lshlrev_b32_e32 v70, 16, v72
	v_add_f32_e32 v70, v58, v70
	v_and_b32_e32 v58, 0xffff0000, v72
	v_add_f32_e32 v71, v59, v58
	v_lshlrev_b32_e32 v58, 16, v73
	v_add_f32_e32 v72, v60, v58
	v_and_b32_e32 v58, 0xffff0000, v73
	v_add_f32_e32 v62, v62, v78
	v_add_f32_e32 v61, v61, v58
	v_mul_f32_e32 v58, v63, v63
	v_mul_f32_e32 v59, v65, v65
	v_fmac_f32_e32 v58, v62, v62
	v_fmac_f32_e32 v59, v64, v64
	v_add_f32_e32 v58, v58, v59
	v_mul_f32_e32 v59, v71, v71
	v_mul_f32_e32 v60, v61, v61
	v_fmac_f32_e32 v59, v70, v70
	v_fmac_f32_e32 v60, v72, v72
	v_add_f32_e32 v59, v59, v60
	v_add_f32_e32 v73, v58, v59
	v_cvt_pk_bf16_f32 v58, v62, v63
	v_cvt_pk_bf16_f32 v59, v64, v65
	v_cvt_pk_bf16_f32 v60, v70, v71
	v_cvt_pk_bf16_f32 v61, v72, v61
	global_store_dwordx4 v[68:69], v[58:61], off
	s_nop 0
	v_lshlrev_b32_e32 v58, 16, v74
	v_add_f32_e32 v54, v54, v58
	v_and_b32_e32 v58, 0xffff0000, v74
	v_add_f32_e32 v55, v55, v58
	v_lshlrev_b32_e32 v58, 16, v75
	v_add_f32_e32 v56, v56, v58
	v_and_b32_e32 v58, 0xffff0000, v75
	v_add_f32_e32 v57, v57, v58
	v_lshlrev_b32_e32 v58, 16, v76
	v_add_f32_e32 v58, v50, v58
	v_and_b32_e32 v50, 0xffff0000, v76
	v_add_f32_e32 v59, v51, v50
	v_lshlrev_b32_e32 v50, 16, v77
	v_add_f32_e32 v60, v52, v50
	v_and_b32_e32 v50, 0xffff0000, v77
	v_add_f32_e32 v53, v53, v50
	v_mul_f32_e32 v50, v55, v55
	v_mul_f32_e32 v51, v57, v57
	v_fmac_f32_e32 v50, v54, v54
	v_fmac_f32_e32 v51, v56, v56
	v_add_f32_e32 v50, v50, v51
	v_mul_f32_e32 v51, v59, v59
	v_mul_f32_e32 v52, v53, v53
	v_fmac_f32_e32 v51, v58, v58
	v_fmac_f32_e32 v52, v60, v60
	v_add_f32_e32 v51, v51, v52
	v_add_f32_e32 v50, v50, v51
	v_add_f32_e32 v61, v73, v50
	v_cvt_pk_bf16_f32 v50, v54, v55
	v_cvt_pk_bf16_f32 v51, v56, v57
	v_cvt_pk_bf16_f32 v52, v58, v59
	v_cvt_pk_bf16_f32 v53, v60, v53
	global_store_dwordx4 v[68:69], v[50:53], off offset:256
	ds_bpermute_b32 v50, v0, v61
	s_waitcnt lgkmcnt(0)
	v_add_f32_e32 v50, v61, v50
	ds_bpermute_b32 v51, v134, v50
	s_waitcnt lgkmcnt(0)
	v_add_f32_e32 v52, v50, v51
	v_lshlrev_b64 v[50:51], 7, v[66:67]
	v_lshl_add_u64 v[50:51], s[0:1], 0, v[50:51]
	global_store_dword v[50:51], v52, off
	v_add_u32_e32 v50, 0x90, v130
	v_ashrrev_i32_e32 v51, 31, v50
	v_lshlrev_b64 v[52:53], 12, v[50:51]
	v_lshl_add_u64 v[52:53], s[4:5], 0, v[52:53]
	v_lshl_add_u64 v[52:53], v[52:53], 0, v[132:133]
	s_waitcnt vmcnt(19)
; __device__ __forceinline__ unsigned cvt_pk_bf16(float lo, float hi) { unsigned r; asm volatile("v_cvt_pk_bf16_f32 %0, %1, %2" : "=v"(r) : "v"(lo), "v"(hi)); return r; }
; __device__ __forceinline__ float bflo(unsigned u) { return __uint_as_float(u << 16); }
; __device__ __forceinline__ float bfhi(unsigned u) { return __uint_as_float(u & 0xffff0000u); }
; __device__ __forceinline__ float shfl_xor_l(float v, int mask, int lane) { return __builtin_bit_cast(float, __builtin_amdgcn_ds_bpermute((lane ^ mask) << 2, __builtin_bit_cast(int, v))); }
; template <bool F32OUT>
; __device__ __forceinline__ void res_epi(const f32x4 (&acc)[2][2][4][2], int pm, int pn, int wr, int wc, int fr, int fq, bf16_t* xb, float* xout, float* ssq_next) {
;     ...
;         for (int m = 0; m < 4; ++m) {
;             const int row = row0 + ai * HALF + m * 16;
;             const size_t off = (size_t)row * D + col0;
;             u32x4 r[2];
; #pragma unroll
;             for (int bj = 0; bj < 2; ++bj) r[bj] = *(const u32x4*)(xb + off + bj * HALF);
;             float s = 0.f;
; #pragma unroll
;             for (int bj = 0; bj < 2; ++bj) {
;                 f32x4 v0 = acc[ai][bj][m][0], v1 = acc[ai][bj][m][1];
;                 v0[0] += bflo(r[bj].x); v0[1] += bfhi(r[bj].x); v0[2] += bflo(r[bj].y); v0[3] += bfhi(r[bj].y);
;                 v1[0] += bflo(r[bj].z); v1[1] += bfhi(r[bj].z); v1[2] += bflo(r[bj].w); v1[3] += bfhi(r[bj].w);
;                 if (F32OUT) { *(f32x4*)(xout + off + bj * HALF) = v0; *(f32x4*)(xout + off + bj * HALF + 4) = v1; }
;                 s += ((v0[0] * v0[0] + v0[1] * v0[1]) + (v0[2] * v0[2] + v0[3] * v0[3])) + ((v1[0] * v1[0] + v1[1] * v1[1]) + (v1[2] * v1[2] + v1[3] * v1[3]));
;                 u32x4 w; w.x = cvt_pk_bf16(v0[0], v0[1]); w.y = cvt_pk_bf16(v0[2], v0[3]); w.z = cvt_pk_bf16(v1[0], v1[1]); w.w = cvt_pk_bf16(v1[2], v1[3]);
;                 if (!F32OUT) *(u32x4*)(xb + off + bj * HALF) = w;
;             }
;             if (!F32OUT) { s += shfl_xor_l(s, 16, ln); s += shfl_xor_l(s, 32, ln);
;                 ssq_next[(size_t)row * 32 + pn * 4 + wc] = s; }
	v_mov_b32_e32 v54, v198
	v_mov_b32_e32 v55, v199
	v_mov_b32_e32 v56, v200
	v_mov_b32_e32 v57, v201
	v_mov_b32_e32 v58, v216
	v_mov_b32_e32 v59, v217
	v_mov_b32_e32 v60, v218
	v_mov_b32_e32 v61, v219
	v_lshlrev_b32_e32 v62, 16, v54
	v_and_b32_e32 v54, 0xffff0000, v54
	v_add_f32_e32 v47, v47, v54
	v_lshlrev_b32_e32 v54, 16, v55
	v_add_f32_e32 v48, v48, v54
	v_and_b32_e32 v54, 0xffff0000, v55
	v_add_f32_e32 v49, v49, v54
	v_lshlrev_b32_e32 v54, 16, v56
	v_add_f32_e32 v54, v42, v54
	v_and_b32_e32 v42, 0xffff0000, v56
	v_add_f32_e32 v55, v43, v42
	v_lshlrev_b32_e32 v42, 16, v57
	v_add_f32_e32 v56, v44, v42
	v_and_b32_e32 v42, 0xffff0000, v57
	v_add_f32_e32 v46, v46, v62
	v_add_f32_e32 v45, v45, v42
	v_mul_f32_e32 v42, v47, v47
	v_mul_f32_e32 v43, v49, v49
	v_fmac_f32_e32 v42, v46, v46
	v_fmac_f32_e32 v43, v48, v48
	v_add_f32_e32 v42, v42, v43
	v_mul_f32_e32 v43, v55, v55
	v_mul_f32_e32 v44, v45, v45
	v_fmac_f32_e32 v43, v54, v54
	v_fmac_f32_e32 v44, v56, v56
	v_add_f32_e32 v43, v43, v44
	v_add_f32_e32 v57, v42, v43
	v_cvt_pk_bf16_f32 v42, v46, v47
	v_cvt_pk_bf16_f32 v43, v48, v49
	v_cvt_pk_bf16_f32 v44, v54, v55
	v_cvt_pk_bf16_f32 v45, v56, v45
	global_store_dwordx4 v[52:53], v[42:45], off
	s_nop 0
	v_lshlrev_b32_e32 v42, 16, v58
	v_add_f32_e32 v38, v38, v42
	v_and_b32_e32 v42, 0xffff0000, v58
	v_add_f32_e32 v39, v39, v42
	v_lshlrev_b32_e32 v42, 16, v59
	v_add_f32_e32 v40, v40, v42
	v_and_b32_e32 v42, 0xffff0000, v59
	v_add_f32_e32 v41, v41, v42
	v_lshlrev_b32_e32 v42, 16, v60
	v_add_f32_e32 v42, v34, v42
	v_and_b32_e32 v34, 0xffff0000, v60
	v_add_f32_e32 v43, v35, v34
	v_lshlrev_b32_e32 v34, 16, v61
	v_add_f32_e32 v44, v36, v34
	v_and_b32_e32 v34, 0xffff0000, v61
	v_add_f32_e32 v37, v37, v34
	v_mul_f32_e32 v34, v39, v39
	v_mul_f32_e32 v35, v41, v41
	v_fmac_f32_e32 v34, v38, v38
	v_fmac_f32_e32 v35, v40, v40
	v_add_f32_e32 v34, v34, v35
	v_mul_f32_e32 v35, v43, v43
	v_mul_f32_e32 v36, v37, v37
	v_fmac_f32_e32 v35, v42, v42
	v_fmac_f32_e32 v36, v44, v44
	v_add_f32_e32 v35, v35, v36
	v_add_f32_e32 v34, v34, v35
	v_add_f32_e32 v45, v57, v34
	v_cvt_pk_bf16_f32 v34, v38, v39
	v_cvt_pk_bf16_f32 v35, v40, v41
	v_cvt_pk_bf16_f32 v36, v42, v43
	v_cvt_pk_bf16_f32 v37, v44, v37
	global_store_dwordx4 v[52:53], v[34:37], off offset:256
	ds_bpermute_b32 v34, v0, v45
	s_waitcnt lgkmcnt(0)
	v_add_f32_e32 v34, v45, v34
	ds_bpermute_b32 v35, v134, v34
	s_waitcnt lgkmcnt(0)
	v_add_f32_e32 v36, v34, v35
	v_lshlrev_b64 v[34:35], 7, v[50:51]
	v_lshl_add_u64 v[34:35], s[0:1], 0, v[34:35]
	global_store_dword v[34:35], v36, off
	v_add_u32_e32 v34, 0xa0, v130
	v_ashrrev_i32_e32 v35, 31, v34
	v_lshlrev_b64 v[36:37], 12, v[34:35]
	v_lshl_add_u64 v[36:37], s[4:5], 0, v[36:37]
	v_lshl_add_u64 v[36:37], v[36:37], 0, v[132:133]
	s_waitcnt vmcnt(20)
	v_mov_b32_e32 v38, v220
	v_mov_b32_e32 v39, v221
	v_mov_b32_e32 v40, v222
	v_mov_b32_e32 v41, v223
	v_mov_b32_e32 v42, v224
	v_mov_b32_e32 v43, v225
	v_mov_b32_e32 v44, v226
	v_mov_b32_e32 v45, v227
	v_lshlrev_b32_e32 v46, 16, v38
	v_and_b32_e32 v38, 0xffff0000, v38
	v_add_f32_e32 v31, v31, v38
	v_lshlrev_b32_e32 v38, 16, v39
	v_add_f32_e32 v32, v32, v38
	v_and_b32_e32 v38, 0xffff0000, v39
	v_add_f32_e32 v33, v33, v38
	v_lshlrev_b32_e32 v38, 16, v40
	v_add_f32_e32 v38, v26, v38
	v_and_b32_e32 v26, 0xffff0000, v40
	v_add_f32_e32 v39, v27, v26
	v_lshlrev_b32_e32 v26, 16, v41
	v_add_f32_e32 v40, v28, v26
	v_and_b32_e32 v26, 0xffff0000, v41
	v_add_f32_e32 v30, v30, v46
	v_add_f32_e32 v29, v29, v26
	v_mul_f32_e32 v26, v31, v31
	v_mul_f32_e32 v27, v33, v33
	v_fmac_f32_e32 v26, v30, v30
	v_fmac_f32_e32 v27, v32, v32
	v_add_f32_e32 v26, v26, v27
	v_mul_f32_e32 v27, v39, v39
	v_mul_f32_e32 v28, v29, v29
	v_fmac_f32_e32 v27, v38, v38
	v_fmac_f32_e32 v28, v40, v40
	v_add_f32_e32 v27, v27, v28
	v_add_f32_e32 v41, v26, v27
	v_cvt_pk_bf16_f32 v26, v30, v31
	v_cvt_pk_bf16_f32 v27, v32, v33
	v_cvt_pk_bf16_f32 v28, v38, v39
	v_cvt_pk_bf16_f32 v29, v40, v29
	global_store_dwordx4 v[36:37], v[26:29], off
	s_nop 0
	v_lshlrev_b32_e32 v26, 16, v42
	v_add_f32_e32 v22, v22, v26
	v_and_b32_e32 v26, 0xffff0000, v42
	v_add_f32_e32 v23, v23, v26
	v_lshlrev_b32_e32 v26, 16, v43
	v_add_f32_e32 v24, v24, v26
	v_and_b32_e32 v26, 0xffff0000, v43
	v_add_f32_e32 v25, v25, v26
	v_lshlrev_b32_e32 v26, 16, v44
	v_add_f32_e32 v26, v18, v26
	v_and_b32_e32 v18, 0xffff0000, v44
	v_add_f32_e32 v27, v19, v18
	v_lshlrev_b32_e32 v18, 16, v45
	v_add_f32_e32 v28, v20, v18
	v_and_b32_e32 v18, 0xffff0000, v45
	v_add_f32_e32 v21, v21, v18
	v_mul_f32_e32 v18, v23, v23
	v_mul_f32_e32 v19, v25, v25
	v_fmac_f32_e32 v18, v22, v22
	v_fmac_f32_e32 v19, v24, v24
	v_add_f32_e32 v18, v18, v19
	v_mul_f32_e32 v19, v27, v27
	v_mul_f32_e32 v20, v21, v21
	v_fmac_f32_e32 v19, v26, v26
	v_fmac_f32_e32 v20, v28, v28
	v_add_f32_e32 v19, v19, v20
	v_add_f32_e32 v18, v18, v19
	v_add_f32_e32 v29, v41, v18
	v_cvt_pk_bf16_f32 v18, v22, v23
	v_cvt_pk_bf16_f32 v19, v24, v25
	v_cvt_pk_bf16_f32 v20, v26, v27
	v_cvt_pk_bf16_f32 v21, v28, v21
	global_store_dwordx4 v[36:37], v[18:21], off offset:256
	ds_bpermute_b32 v18, v0, v29
	s_waitcnt lgkmcnt(0)
; __device__ __forceinline__ unsigned cvt_pk_bf16(float lo, float hi) { unsigned r; asm volatile("v_cvt_pk_bf16_f32 %0, %1, %2" : "=v"(r) : "v"(lo), "v"(hi)); return r; }
; __device__ __forceinline__ float bflo(unsigned u) { return __uint_as_float(u << 16); }
; __device__ __forceinline__ float bfhi(unsigned u) { return __uint_as_float(u & 0xffff0000u); }
; __device__ __forceinline__ float shfl_xor_l(float v, int mask, int lane) { return __builtin_bit_cast(float, __builtin_amdgcn_ds_bpermute((lane ^ mask) << 2, __builtin_bit_cast(int, v))); }
; template <bool F32OUT>
; __device__ __forceinline__ void res_epi(const f32x4 (&acc)[2][2][4][2], int pm, int pn, int wr, int wc, int fr, int fq, bf16_t* xb, float* xout, float* ssq_next) {
;     ...
;         for (int m = 0; m < 4; ++m) {
;             const int row = row0 + ai * HALF + m * 16;
;             const size_t off = (size_t)row * D + col0;
;             u32x4 r[2];
; #pragma unroll
;             for (int bj = 0; bj < 2; ++bj) r[bj] = *(const u32x4*)(xb + off + bj * HALF);
;             float s = 0.f;
; #pragma unroll
;             for (int bj = 0; bj < 2; ++bj) {
;                 f32x4 v0 = acc[ai][bj][m][0], v1 = acc[ai][bj][m][1];
;                 v0[0] += bflo(r[bj].x); v0[1] += bfhi(r[bj].x); v0[2] += bflo(r[bj].y); v0[3] += bfhi(r[bj].y);
;                 v1[0] += bflo(r[bj].z); v1[1] += bfhi(r[bj].z); v1[2] += bflo(r[bj].w); v1[3] += bfhi(r[bj].w);
;                 if (F32OUT) { *(f32x4*)(xout + off + bj * HALF) = v0; *(f32x4*)(xout + off + bj * HALF + 4) = v1; }
;                 s += ((v0[0] * v0[0] + v0[1] * v0[1]) + (v0[2] * v0[2] + v0[3] * v0[3])) + ((v1[0] * v1[0] + v1[1] * v1[1]) + (v1[2] * v1[2] + v1[3] * v1[3]));
;                 u32x4 w; w.x = cvt_pk_bf16(v0[0], v0[1]); w.y = cvt_pk_bf16(v0[2], v0[3]); w.z = cvt_pk_bf16(v1[0], v1[1]); w.w = cvt_pk_bf16(v1[2], v1[3]);
;                 if (!F32OUT) *(u32x4*)(xb + off + bj * HALF) = w;
;             }
;             if (!F32OUT) { s += shfl_xor_l(s, 16, ln); s += shfl_xor_l(s, 32, ln);
;                 ssq_next[(size_t)row * 32 + pn * 4 + wc] = s; }
	v_add_f32_e32 v18, v29, v18
	ds_bpermute_b32 v19, v134, v18
	s_waitcnt lgkmcnt(0)
	v_add_f32_e32 v20, v18, v19
	v_lshlrev_b64 v[18:19], 7, v[34:35]
	v_lshl_add_u64 v[18:19], s[0:1], 0, v[18:19]
	global_store_dword v[18:19], v20, off
	v_add_u32_e32 v18, 0xb0, v130
	v_ashrrev_i32_e32 v19, 31, v18
	v_lshlrev_b64 v[20:21], 12, v[18:19]
	v_lshl_add_u64 v[20:21], s[4:5], 0, v[20:21]
	v_lshl_add_u64 v[20:21], v[20:21], 0, v[132:133]
	s_waitcnt vmcnt(21)
	v_mov_b32_e32 v22, v228
	v_mov_b32_e32 v23, v229
	v_mov_b32_e32 v24, v230
	v_mov_b32_e32 v25, v231
	v_mov_b32_e32 v26, v232
	v_mov_b32_e32 v27, v233
	v_mov_b32_e32 v28, v234
	v_mov_b32_e32 v29, v235
	v_lshlrev_b32_e32 v30, 16, v22
	v_and_b32_e32 v22, 0xffff0000, v22
	v_add_f32_e32 v15, v15, v22
	v_lshlrev_b32_e32 v22, 16, v23
	v_add_f32_e32 v16, v16, v22
	v_and_b32_e32 v22, 0xffff0000, v23
	v_add_f32_e32 v17, v17, v22
	v_lshlrev_b32_e32 v22, 16, v24
	v_add_f32_e32 v22, v10, v22
	v_and_b32_e32 v10, 0xffff0000, v24
	v_add_f32_e32 v23, v11, v10
	v_lshlrev_b32_e32 v10, 16, v25
	v_add_f32_e32 v24, v12, v10
	v_and_b32_e32 v10, 0xffff0000, v25
	v_add_f32_e32 v14, v14, v30
	v_add_f32_e32 v13, v13, v10
	v_mul_f32_e32 v10, v15, v15
	v_mul_f32_e32 v11, v17, v17
	v_fmac_f32_e32 v10, v14, v14
	v_fmac_f32_e32 v11, v16, v16
	v_add_f32_e32 v10, v10, v11
	v_mul_f32_e32 v11, v23, v23
	v_mul_f32_e32 v12, v13, v13
	v_fmac_f32_e32 v11, v22, v22
	v_fmac_f32_e32 v12, v24, v24
	v_add_f32_e32 v11, v11, v12
	v_add_f32_e32 v25, v10, v11
	v_cvt_pk_bf16_f32 v10, v14, v15
	v_cvt_pk_bf16_f32 v11, v16, v17
	v_cvt_pk_bf16_f32 v12, v22, v23
	v_cvt_pk_bf16_f32 v13, v24, v13
	global_store_dwordx4 v[20:21], v[10:13], off
	s_nop 0
	v_lshlrev_b32_e32 v10, 16, v26
	v_add_f32_e32 v6, v6, v10
	v_and_b32_e32 v10, 0xffff0000, v26
	v_add_f32_e32 v7, v7, v10
	v_lshlrev_b32_e32 v10, 16, v27
	v_add_f32_e32 v8, v8, v10
	v_and_b32_e32 v10, 0xffff0000, v27
	v_add_f32_e32 v9, v9, v10
	v_lshlrev_b32_e32 v10, 16, v28
	v_add_f32_e32 v10, v2, v10
	v_and_b32_e32 v2, 0xffff0000, v28
	v_add_f32_e32 v11, v3, v2
	v_lshlrev_b32_e32 v2, 16, v29
	v_add_f32_e32 v12, v4, v2
	v_and_b32_e32 v2, 0xffff0000, v29
	v_add_f32_e32 v5, v5, v2
	v_mul_f32_e32 v2, v7, v7
	v_mul_f32_e32 v3, v9, v9
	v_fmac_f32_e32 v2, v6, v6
	v_fmac_f32_e32 v3, v8, v8
	v_add_f32_e32 v2, v2, v3
	v_mul_f32_e32 v3, v11, v11
	v_mul_f32_e32 v4, v5, v5
	v_fmac_f32_e32 v3, v10, v10
	v_fmac_f32_e32 v4, v12, v12
	v_add_f32_e32 v3, v3, v4
	v_add_f32_e32 v2, v2, v3
	v_add_f32_e32 v13, v25, v2
	ds_bpermute_b32 v0, v0, v13
	v_cvt_pk_bf16_f32 v2, v6, v7
	v_cvt_pk_bf16_f32 v3, v8, v9
	v_cvt_pk_bf16_f32 v4, v10, v11
	v_cvt_pk_bf16_f32 v5, v12, v5
	s_waitcnt lgkmcnt(0)
	v_add_f32_e32 v0, v13, v0
	global_store_dwordx4 v[20:21], v[2:5], off offset:256
	ds_bpermute_b32 v2, v134, v0
	s_waitcnt lgkmcnt(0)
	v_add_f32_e32 v0, v0, v2
	v_lshlrev_b64 v[2:3], 7, v[18:19]
	v_lshl_add_u64 v[2:3], s[0:1], 0, v[2:3]
	global_store_dword v[2:3], v0, off

; __device__ __forceinline__ unsigned cvt_pk_bf16(float lo, float hi) { unsigned r; asm volatile("v_cvt_pk_bf16_f32 %0, %1, %2" : "=v"(r) : "v"(lo), "v"(hi)); return r; }
; __device__ __forceinline__ void transpose_item(const float* W, int K, int N, const float* g0, const float* g1, bf16_t* WT, LAS unsigned* T, int item, int lane, bool gate_up_interleave = false, bool rope_heads = false) {
;     ...
;     const float* wp = W + (size_t)(k0 + kh) * N + n0 + 4 * l31;
; #pragma unroll 4
;     for (int i = 0; i < 16; ++i) {
;         const int kk = 4 * i + kh;
;         f32x4 va = __builtin_nontemporal_load((const f32x4*)(wp + (size_t)(4 * i) * N)), vb = __builtin_nontemporal_load((const f32x4*)(wp + (size_t)(4 * i + 1) * N));
;         if (gp) { va = va * gp[kk]; vb = vb * gp[kk + 1]; }
; #pragma unroll
;         for (int e = 0; e < 4; ++e) T[(4 * l31 + e) * PD + (kk >> 1)] = cvt_pk_bf16(va[e], vb[e]);
;     }
.LBB0_289:
	s_add_u32 s100, s72, s74
	s_addc_u32 s101, s73, s75
	v_lshl_add_u64 v[48:49], v[30:31], 0, s[72:73]
	v_lshl_add_u64 v[50:51], v[16:17], 0, s[72:73]
	global_load_dwordx4 v[64:67], v[48:49], off nt
	global_load_dwordx4 v[68:71], v[50:51], off nt
	v_lshl_add_u64 v[48:49], v[18:19], 0, s[72:73]
	v_lshl_add_u64 v[50:51], v[20:21], 0, s[72:73]
	global_load_dwordx4 v[72:75], v[48:49], off nt
	global_load_dwordx4 v[76:79], v[50:51], off nt
	v_lshl_add_u64 v[48:49], v[22:23], 0, s[72:73]
	v_lshl_add_u64 v[50:51], v[24:25], 0, s[72:73]
	global_load_dwordx4 v[80:83], v[48:49], off nt
	global_load_dwordx4 v[84:87], v[50:51], off nt
	v_lshl_add_u64 v[48:49], v[26:27], 0, s[72:73]
	v_lshl_add_u64 v[50:51], v[28:29], 0, s[72:73]
	global_load_dwordx4 v[88:91], v[48:49], off nt
	global_load_dwordx4 v[92:95], v[50:51], off nt
	v_lshl_add_u64 v[48:49], v[30:31], 0, s[100:101]
	v_lshl_add_u64 v[50:51], v[16:17], 0, s[100:101]
	global_load_dwordx4 v[96:99], v[48:49], off nt
	global_load_dwordx4 v[100:103], v[50:51], off nt
	v_lshl_add_u64 v[48:49], v[18:19], 0, s[100:101]
	v_lshl_add_u64 v[50:51], v[20:21], 0, s[100:101]
	global_load_dwordx4 v[104:107], v[48:49], off nt
	global_load_dwordx4 v[108:111], v[50:51], off nt
	v_lshl_add_u64 v[48:49], v[22:23], 0, s[100:101]
	v_lshl_add_u64 v[50:51], v[24:25], 0, s[100:101]
	global_load_dwordx4 v[112:115], v[48:49], off nt
	global_load_dwordx4 v[116:119], v[50:51], off nt
	v_lshl_add_u64 v[48:49], v[26:27], 0, s[100:101]
	v_lshl_add_u64 v[50:51], v[28:29], 0, s[100:101]
	global_load_dwordx4 v[120:123], v[48:49], off nt
	global_load_dwordx4 v[124:127], v[50:51], off nt
	v_lshl_add_u64 v[32:33], v[14:15], 0, s[66:67]
	s_andn2_b64 vcc, exec, s[70:71]
	s_cbranch_vccnz .Ltri_nog
	global_load_dwordx2 v[128:129], v[32:33], off
	global_load_dwordx2 v[130:131], v[32:33], off offset:16
	global_load_dwordx2 v[132:133], v[32:33], off offset:32
	global_load_dwordx2 v[134:135], v[32:33], off offset:48
	global_load_dwordx2 v[136:137], v[32:33], off offset:64
	global_load_dwordx2 v[138:139], v[32:33], off offset:80
	global_load_dwordx2 v[140:141], v[32:33], off offset:96
	global_load_dwordx2 v[142:143], v[32:33], off offset:112
	s_waitcnt vmcnt(0)
	v_pk_mul_f32 v[66:67], v[66:67], v[128:129] op_sel_hi:[1,0]
	v_pk_mul_f32 v[64:65], v[64:65], v[128:129] op_sel_hi:[1,0]
	v_pk_mul_f32 v[70:71], v[70:71], v[128:129] op_sel:[0,1]
	v_pk_mul_f32 v[68:69], v[68:69], v[128:129] op_sel:[0,1]
	v_pk_mul_f32 v[74:75], v[74:75], v[130:131] op_sel_hi:[1,0]
	v_pk_mul_f32 v[72:73], v[72:73], v[130:131] op_sel_hi:[1,0]
	v_pk_mul_f32 v[78:79], v[78:79], v[130:131] op_sel:[0,1]
	v_pk_mul_f32 v[76:77], v[76:77], v[130:131] op_sel:[0,1]
	v_pk_mul_f32 v[82:83], v[82:83], v[132:133] op_sel_hi:[1,0]
	v_pk_mul_f32 v[80:81], v[80:81], v[132:133] op_sel_hi:[1,0]
	v_pk_mul_f32 v[86:87], v[86:87], v[132:133] op_sel:[0,1]
	v_pk_mul_f32 v[84:85], v[84:85], v[132:133] op_sel:[0,1]
	v_pk_mul_f32 v[90:91], v[90:91], v[134:135] op_sel_hi:[1,0]
	v_pk_mul_f32 v[88:89], v[88:89], v[134:135] op_sel_hi:[1,0]
	v_pk_mul_f32 v[94:95], v[94:95], v[134:135] op_sel:[0,1]
	v_pk_mul_f32 v[92:93], v[92:93], v[134:135] op_sel:[0,1]
	v_pk_mul_f32 v[98:99], v[98:99], v[136:137] op_sel_hi:[1,0]
	v_pk_mul_f32 v[96:97], v[96:97], v[136:137] op_sel_hi:[1,0]
	v_pk_mul_f32 v[102:103], v[102:103], v[136:137] op_sel:[0,1]
	v_pk_mul_f32 v[100:101], v[100:101], v[136:137] op_sel:[0,1]
	v_pk_mul_f32 v[106:107], v[106:107], v[138:139] op_sel_hi:[1,0]
	v_pk_mul_f32 v[104:105], v[104:105], v[138:139] op_sel_hi:[1,0]
	v_pk_mul_f32 v[110:111], v[110:111], v[138:139] op_sel:[0,1]
	v_pk_mul_f32 v[108:109], v[108:109], v[138:139] op_sel:[0,1]
	v_pk_mul_f32 v[114:115], v[114:115], v[140:141] op_sel_hi:[1,0]
	v_pk_mul_f32 v[112:113], v[112:113], v[140:141] op_sel_hi:[1,0]
	v_pk_mul_f32 v[118:119], v[118:119], v[140:141] op_sel:[0,1]
	v_pk_mul_f32 v[116:117], v[116:117], v[140:141] op_sel:[0,1]
	v_pk_mul_f32 v[122:123], v[122:123], v[142:143] op_sel_hi:[1,0]
	v_pk_mul_f32 v[120:121], v[120:121], v[142:143] op_sel_hi:[1,0]
	v_pk_mul_f32 v[126:127], v[126:127], v[142:143] op_sel:[0,1]
	v_pk_mul_f32 v[124:125], v[124:125], v[142:143] op_sel:[0,1]
.Ltri_nog:
	s_waitcnt vmcnt(0)
	v_cvt_pk_bf16_f32 v2, v64, v68
	ds_write_b32 v44, v2
	v_cvt_pk_bf16_f32 v3, v65, v69
	ds_write_b32 v44, v3 offset:144
	v_cvt_pk_bf16_f32 v4, v66, v70
	ds_write_b32 v44, v4 offset:288
	v_cvt_pk_bf16_f32 v5, v67, v71
	ds_write_b32 v44, v5 offset:432
	v_cvt_pk_bf16_f32 v2, v72, v76
	ds_write_b32 v44, v2 offset:8
	v_cvt_pk_bf16_f32 v3, v73, v77
	ds_write_b32 v44, v3 offset:152
	v_cvt_pk_bf16_f32 v4, v74, v78
	ds_write_b32 v44, v4 offset:296
	v_cvt_pk_bf16_f32 v5, v75, v79
	ds_write_b32 v44, v5 offset:440
	v_cvt_pk_bf16_f32 v2, v80, v84
	ds_write_b32 v44, v2 offset:16
	v_cvt_pk_bf16_f32 v3, v81, v85
	ds_write_b32 v44, v3 offset:160
	v_cvt_pk_bf16_f32 v4, v82, v86
	ds_write_b32 v44, v4 offset:304
	v_cvt_pk_bf16_f32 v5, v83, v87
	ds_write_b32 v44, v5 offset:448
	v_cvt_pk_bf16_f32 v2, v88, v92
	ds_write_b32 v44, v2 offset:24
	v_cvt_pk_bf16_f32 v3, v89, v93
	ds_write_b32 v44, v3 offset:168
	v_cvt_pk_bf16_f32 v4, v90, v94
	ds_write_b32 v44, v4 offset:312
	v_cvt_pk_bf16_f32 v5, v91, v95
	ds_write_b32 v44, v5 offset:456
	v_cvt_pk_bf16_f32 v2, v96, v100
	ds_write_b32 v44, v2 offset:32
	v_cvt_pk_bf16_f32 v3, v97, v101
	ds_write_b32 v44, v3 offset:176
	v_cvt_pk_bf16_f32 v4, v98, v102
	ds_write_b32 v44, v4 offset:320
	v_cvt_pk_bf16_f32 v5, v99, v103
	ds_write_b32 v44, v5 offset:464
	v_cvt_pk_bf16_f32 v2, v104, v108
	ds_write_b32 v44, v2 offset:40
	v_cvt_pk_bf16_f32 v3, v105, v109
	ds_write_b32 v44, v3 offset:184
	v_cvt_pk_bf16_f32 v4, v106, v110
	ds_write_b32 v44, v4 offset:328
	v_cvt_pk_bf16_f32 v5, v107, v111
	ds_write_b32 v44, v5 offset:472
	v_cvt_pk_bf16_f32 v2, v112, v116
	ds_write_b32 v44, v2 offset:48
	v_cvt_pk_bf16_f32 v3, v113, v117
	ds_write_b32 v44, v3 offset:192
	v_cvt_pk_bf16_f32 v4, v114, v118
	ds_write_b32 v44, v4 offset:336
	v_cvt_pk_bf16_f32 v5, v115, v119
	ds_write_b32 v44, v5 offset:480
	v_cvt_pk_bf16_f32 v2, v120, v124
	ds_write_b32 v44, v2 offset:56
	v_cvt_pk_bf16_f32 v3, v121, v125
	ds_write_b32 v44, v3 offset:200
	v_cvt_pk_bf16_f32 v4, v122, v126
	ds_write_b32 v44, v4 offset:344
	v_cvt_pk_bf16_f32 v5, v123, v127
	ds_write_b32 v44, v5 offset:488
	s_lshl_b64 s[100:101], s[74:75], 1
	s_add_u32 s66, s66, 0x80
	s_addc_u32 s67, s67, 0
	v_add_u32_e32 v44, 64, v44
	v_lshl_add_u64 v[16:17], v[16:17], 0, s[100:101]
	v_lshl_add_u64 v[18:19], v[18:19], 0, s[100:101]
	v_lshl_add_u64 v[20:21], v[20:21], 0, s[100:101]
	v_lshl_add_u64 v[22:23], v[22:23], 0, s[100:101]
	v_lshl_add_u64 v[24:25], v[24:25], 0, s[100:101]
	v_lshl_add_u64 v[26:27], v[26:27], 0, s[100:101]
	v_lshl_add_u64 v[28:29], v[28:29], 0, s[100:101]
	v_lshl_add_u64 v[30:31], v[30:31], 0, s[100:101]
	s_cmpk_eq_i32 s66, 0x100
	s_cbranch_scc0 .LBB0_289

; __global__ void __launch_bounds__(NTHREADS, 2) fwd_kernel(Args a) {
	.amdhsa_kernel _Z10fwd_kernel4Args
		.amdhsa_group_segment_fixed_size 0
		.amdhsa_private_segment_fixed_size 0
		.amdhsa_kernarg_size 424
		.amdhsa_user_sgpr_count 2
		.amdhsa_user_sgpr_dispatch_ptr 0
		.amdhsa_user_sgpr_queue_ptr 0
		.amdhsa_user_sgpr_kernarg_segment_ptr 1
		.amdhsa_user_sgpr_dispatch_id 0
		.amdhsa_user_sgpr_kernarg_preload_length 0
		.amdhsa_user_sgpr_kernarg_preload_offset 0
		.amdhsa_user_sgpr_private_segment_size 0
		.amdhsa_uses_dynamic_stack 0
		.amdhsa_enable_private_segment 0
		.amdhsa_system_sgpr_workgroup_id_x 1
		.amdhsa_system_sgpr_workgroup_id_y 0
		.amdhsa_system_sgpr_workgroup_id_z 0
		.amdhsa_system_sgpr_workgroup_info 0
		.amdhsa_system_vgpr_workitem_id 2
		.amdhsa_next_free_vgpr 239
		.amdhsa_next_free_sgpr 102
		.amdhsa_accum_offset 240
		.amdhsa_reserve_vcc 1
		.amdhsa_float_round_mode_32 0
		.amdhsa_float_round_mode_16_64 0
		.amdhsa_float_denorm_mode_32 3
		.amdhsa_float_denorm_mode_16_64 3
		.amdhsa_dx10_clamp 1
		.amdhsa_ieee_mode 1
		.amdhsa_fp16_overflow 0
		.amdhsa_tg_split 0
		.amdhsa_exception_fp_ieee_invalid_op 0
		.amdhsa_exception_fp_denorm_src 0
		.amdhsa_exception_fp_ieee_div_zero 0
		.amdhsa_exception_fp_ieee_overflow 0
		.amdhsa_exception_fp_ieee_underflow 0
		.amdhsa_exception_fp_ieee_inexact 0
		.amdhsa_exception_int_div_zero 0
	.end_amdhsa_kernel

; __global__ void __launch_bounds__(NTHREADS, 2) fwd_kernel(Args a) {
amdhsa.kernels:
  - .agpr_count:     0
    .args:
      - .offset:         0
        .size:           168
        .value_kind:     by_value
      - .offset:         168
        .size:           4
        .value_kind:     hidden_block_count_x
      - .offset:         172
        .size:           4
        .value_kind:     hidden_block_count_y
      - .offset:         176
        .size:           4
        .value_kind:     hidden_block_count_z
      - .offset:         180
        .size:           2
        .value_kind:     hidden_group_size_x
      - .offset:         182
        .size:           2
        .value_kind:     hidden_group_size_y
      - .offset:         184
        .size:           2
        .value_kind:     hidden_group_size_z
      - .offset:         186
        .size:           2
        .value_kind:     hidden_remainder_x
      - .offset:         188
        .size:           2
        .value_kind:     hidden_remainder_y
      - .offset:         190
        .size:           2
        .value_kind:     hidden_remainder_z
      - .offset:         208
        .size:           8
        .value_kind:     hidden_global_offset_x
      - .offset:         216
        .size:           8
        .value_kind:     hidden_global_offset_y
      - .offset:         224
        .size:           8
        .value_kind:     hidden_global_offset_z
      - .offset:         232
        .size:           2
        .value_kind:     hidden_grid_dims
      - .offset:         256
        .size:           8
        .value_kind:     hidden_multigrid_sync_arg
      - .offset:         288
        .size:           4
        .value_kind:     hidden_dynamic_lds_size
    .group_segment_fixed_size: 0
    .kernarg_segment_align: 8
    .kernarg_segment_size: 424
    .language:       OpenCL C
    .language_version:
      - 2
      - 0
    .max_flat_workgroup_size: 512
    .name:           _Z10fwd_kernel4Args
    .private_segment_fixed_size: 0
    .sgpr_count:     108
    .sgpr_spill_count: 190
    .symbol:         _Z10fwd_kernel4Args.kd
    .uniform_work_group_size: 1
    .uses_dynamic_stack: false
    .vgpr_count:     239
    .vgpr_spill_count: 0
    .wavefront_size: 64
